# up-proj gate epilogue rewritten: in-lane row map (grid row 8fr+g), packed FMA conv, loads hoisted
# speedup vs baseline: 1.3256x; 1.3256x over previous
;     __host__ __device__ bool next(int i, Unit& u) const { const long L = (long)i * G + c; if (L >= nwg) return false; u.pm = 0; u.pn = c % nN; return true; }
; #define PG8_WAIT_V(n) asm volatile("s_waitcnt vmcnt(" #n ")" ::: "memory")
; #define PG8_BAR __builtin_amdgcn_s_barrier()
; template <class Epi, class Sched, bool ALIGN_EPI = false, bool SP2 = false, bool F8 = false>
; __device__ __forceinline__ void gemm_phase(PG8_LAS unsigned char* lds, const Gemm g, const Sched& S, const Epi& E) {
;     const int tid = threadIdx.x, wid = __builtin_amdgcn_readfirstlane(tid >> 6), lane = tid & 63, wr = wid >> 2, wc = wid & 3, fr = lane & 15, fq = lane >> 4;
;     const int K = g.K, nt = K / BK;
;     unsigned voffA[2], voffB[2];
; #pragma unroll
;     for (int i = 0; i < 2; ++i) { int R, C; stage_rc(tid * 16 + i * 8192, R, C); const int Rb = Epi::PERM ? ((R & ~31) + perm32(R & 31)) : R;
;         const int Ra = Epi::GRIDMAP ? ((R & 63) * 64 + (R >> 6)) : R;
;         voffA[i] = (unsigned)(Ra * K + C) * 2u; voffB[i] = (unsigned)(Rb * K + C) * 2u; }
;     const size_t kstep = (size_t)(BK * 2);
;     const size_t hstep = (size_t)HALF * K * 2;
;     const size_t tstep = 2 * hstep;
;     const size_t hstepA = Epi::GRIDMAP ? (size_t)4096 * K * 2 : hstep;
;     ...
;     const unsigned ldsw = (unsigned)wid * 1024u;
;     const int aoff = lds_byte(wr * 64 + fr, fq * 8), boff = lds_byte(wc * 32 + fr, fq * 8);
;     ...
;     Unit cur, nxt; int ui = 0;
;     if (!S.next(0, cur)) return;
;     f32x4 acc[2][2][4][2];
; #pragma unroll
;     for (int a = 0; a < 2; ++a)
; #pragma unroll
;         for (int b = 0; b < 2; ++b)
; #pragma unroll
;             for (int m = 0; m < 4; ++m)
; #pragma unroll
;                 for (int n = 0; n < 2; ++n) acc[a][b][m][n] = (f32x4){0.f, 0.f, 0.f, 0.f};
;     bf16x8 At[4][2], B0[2][2], B1[2][2];
;     const char* cA = PG8_ABASE(cur.pm); const char* cB = (const char*)g.Bt + (size_t)cur.pn * tstep;
;     S.a_ready(cur);
;     if constexpr (SP2) {
;         PG8_STAGE(PG8_SB(0, 0), cB, voffB); PG8_STAGE(PG8_SB(0, 1), cB + hstep, voffB); PG8_STAGE(PG8_SA(0, 0), cA, voffA); PG8_STAGE(PG8_SA(0, 1), cA + hstepA, voffA);
;         if (wr == 1) PG8_BAR;
;         PG8_WAIT_V(2); PG8_BAR;
;         PG8_STAGE(PG8_SB(1, 0), cB + kstep, voffB); PG8_STAGE(PG8_SA(1, 0), cA + kstep, voffA); PG8_STAGE(PG8_SB(1, 1), cB + hstep + kstep, voffB);
;         PG8_WAIT_V(6); PG8_BAR;
.LBB0_906:
	s_or_b64 exec, exec, s[4:5]
	s_cmpk_lt_i32 s2, 0xb00
	v_readfirstlane_b32 s5, v0
	s_waitcnt lgkmcnt(0)
	s_barrier
	s_cbranch_scc0 .LBB0_924
	v_lshrrev_b32_e32 v2, 5, v0
	v_and_b32_e32 v2, 4, v2
	v_bfe_u32 v3, v0, 2, 2
	v_and_b32_e32 v1, 24, v1
	v_or3_b32 v2, v2, v3, v1
	v_lshlrev_b32_e32 v1, 4, v0
	s_waitcnt vmcnt(4)
	v_or_b32_e32 v10, 0x2000, v1
	v_lshrrev_b32_e32 v3, 7, v10
	s_movk_i32 s4, 0x60
	s_ashr_i32 s63, s2, 31
	v_and_or_b32 v4, v3, s4, v2
	s_lshr_b32 s4, s63, 29
	s_add_i32 s4, s2, s4
	s_lshr_b32 s6, s5, 6
	s_ashr_i32 s7, s4, 3
	s_and_b32 s4, s4, -8
	s_lshr_b32 s23, s5, 8
	s_lshl_b32 s62, s6, 10
	s_sub_i32 s4, s2, s4
	s_cmp_lt_i32 s4, 0
	s_movk_i32 s64, 0x161
	s_cselect_b32 s8, s64, 0x160
	s_mul_i32 s4, s4, s8
	s_add_i32 s4, s4, s7
	s_mul_hi_i32 s7, s4, 0x2e8ba2e9
	s_lshr_b32 s8, s7, 31
	s_ashr_i32 s7, s7, 6
	s_add_i32 s7, s7, s8
	s_lshl_b32 s8, s7, 3
	s_mulk_i32 s7, 0x160
	s_sub_i32 s7, s4, s7
	s_sext_i32_i16 s4, s7
	s_bfe_u32 s4, s4, 0x3001c
	s_add_i32 s9, s7, s4
	s_sext_i32_i16 s4, s9
	s_and_b32 s9, s9, 0xfff8
	s_sub_i32 s7, s7, s9
	s_sext_i32_i16 s7, s7
	s_add_i32 s84, s8, s7
	s_lshl_b32 s7, s84, 8
	s_lshl_b32 s8, s84, 1
	s_and_b32 s7, s7, 0xffffe000
	s_and_b32 s8, s8, 62
	v_and_b32_e32 v5, 32, v0
	v_bfe_u32 v13, v0, 2, 4
	s_lshr_b32 s4, s4, 3
	s_or_b32 s8, s7, s8
	v_bitop3_b32 v11, v1, v5, 48 bitop3:0x6c
	v_and_b32_e32 v12, 64, v0
	v_bfe_u32 v1, v3, 4, 2
	v_lshl_or_b32 v1, v13, 3, v1
	s_ashr_i32 s9, s8, 31
	s_bfe_i64 s[10:11], s[4:5], 0x100000
	v_or_b32_e32 v5, v11, v12
	v_lshlrev_b32_e32 v3, 18, v1
	v_mov_b32_e32 v1, 0x1000
	s_lshl_b64 s[8:9], s[8:9], 12
	s_lshl_b64 s[10:11], s[10:11], 20
	v_or3_b32 v132, v3, v5, v1
	v_lshrrev_b32_e32 v3, 3, v0
	s_add_u32 s58, s42, s10
	v_and_or_b32 v2, v3, 32, v2
	s_addc_u32 s59, s43, s11
	s_add_i32 s65, s62, 0
	v_lshl_or_b32 v134, v2, 12, v5
	s_add_i32 m0, s65, 0x10000
	v_lshl_or_b32 v130, v4, 12, v5
	global_load_lds_dwordx4 v134, s[58:59]
	s_add_i32 m0, s65, 0x12000
	s_add_u32 s10, s58, 0x80000
	global_load_lds_dwordx4 v130, s[58:59]
	s_addc_u32 s11, s59, 0
	s_add_i32 m0, s65, 0x14000
	v_bfe_u32 v2, v3, 4, 2
	v_lshl_or_b32 v2, v13, 3, v2
	global_load_lds_dwordx4 v134, s[10:11]
	s_add_i32 m0, s65, 0x16000
	s_add_u32 s56, s30, s8
	s_addc_u32 s57, s31, s9
	s_add_i32 s66, s65, 0x2000
	s_waitcnt vmcnt(0)
	v_lshl_or_b32 v136, v2, 18, v5
	global_load_lds_dwordx4 v130, s[10:11]
	s_mov_b32 m0, s65
	s_add_u32 s8, s56, 0x100000
	global_load_lds_dwordx4 v136, s[56:57]
	s_mov_b32 m0, s66
	s_addc_u32 s9, s57, 0
	s_add_i32 s67, s65, 0x4000
	global_load_lds_dwordx4 v132, s[56:57]
	s_mov_b32 m0, s67
	s_add_i32 s68, s65, 0x6000
	global_load_lds_dwordx4 v136, s[8:9]
	s_mov_b32 m0, s68
	v_mov_b32_e32 v135, 0
	global_load_lds_dwordx4 v132, s[8:9]
	s_load_dwordx4 s[8:11], s[0:1], 0x70
	v_mov_b32_e32 v131, v135
	v_mov_b32_e32 v137, v135
	v_mov_b32_e32 v133, v135
	s_cmp_eq_u32 s23, 1
	s_mov_b32 s69, 0
	v_lshl_add_u64 v[8:9], s[58:59], 0, v[134:135]
	v_lshl_add_u64 v[6:7], s[58:59], 0, v[130:131]
	v_lshl_add_u64 v[2:3], s[56:57], 0, v[136:137]
	s_cselect_b64 s[12:13], -1, 0
	s_cmp_lg_u32 s23, 1
	v_lshl_add_u64 v[4:5], s[56:57], 0, v[132:133]
	s_cbranch_scc1 .LBB0_909
	s_barrier
.LBB0_909:
	s_lshl_b32 s6, s6, 5
	s_mov_b64 s[40:41], 0x80
	s_and_b32 s70, s6, 0x60
	s_add_i32 m0, s65, 0x18000
	v_lshl_add_u64 v[8:9], v[8:9], 0, s[40:41]
	s_lshl_b32 s14, s23, 13
	s_lshl_b32 s15, s70, 7
	s_waitcnt vmcnt(2)
	s_barrier
	global_load_lds_dwordx4 v[8:9], off
	v_lshl_add_u64 v[6:7], v[6:7], 0, s[40:41]
	s_add_i32 m0, s65, 0x1a000
	s_add_i32 s71, s65, 0x8000
	s_add_i32 s72, s65, 0xa000
	global_load_lds_dwordx4 v[6:7], off
	v_lshl_add_u64 v[2:3], v[2:3], 0, s[40:41]
	s_mov_b32 m0, s71
	s_add_u32 s6, s58, 0x80080
	global_load_lds_dwordx4 v[2:3], off
	v_lshl_add_u64 v[2:3], v[4:5], 0, s[40:41]
	s_mov_b32 m0, s72
	s_addc_u32 s7, s59, 0
	global_load_lds_dwordx4 v[2:3], off
	s_add_i32 m0, s65, 0x1c000
	v_lshl_add_u64 v[2:3], s[6:7], 0, v[134:135]
	global_load_lds_dwordx4 v[2:3], off
	v_lshl_add_u64 v[2:3], s[6:7], 0, v[130:131]
	s_add_i32 m0, s65, 0x1e000
	v_bfe_u32 v173, v0, 4, 2
	global_load_lds_dwordx4 v[2:3], off
	v_and_b32_e32 v172, 15, v0
	v_lshlrev_b32_e32 v2, 4, v173
	v_lshlrev_b32_e32 v4, 2, v0
	v_lshl_or_b32 v3, v172, 6, v2
	v_and_b32_e32 v4, 32, v4
	v_bitop3_b32 v5, s14, v3, v4 bitop3:0xf6
	v_lshlrev_b32_e32 v3, 6, v0
	s_movk_i32 s6, 0x3c0
	s_cmpk_lt_u32 s5, 0x100
	v_and_or_b32 v2, v3, s6, v2
	s_sext_i32_i16 s14, s4
	s_cselect_b64 s[44:45], -1, 0
	s_and_b32 s4, s5, 0xffffff00
	s_ashr_i32 s73, s90, 31
	v_bitop3_b32 v174, s15, v2, v4 bitop3:0xf6
	s_waitcnt lgkmcnt(0)
	s_add_u32 s46, s8, 0x5800
	v_lshlrev_b32_e32 v2, 11, v0
	s_addc_u32 s47, s9, 0
	v_and_b32_e32 v2, 0xc0000, v2
	v_lshlrev_b32_e32 v4, 21, v13
	s_add_u32 s48, s8, 0xb000
	v_or3_b32 v2, v11, v2, v4
	s_addc_u32 s49, s9, 0
	s_add_i32 s74, s4, 0
	v_add_u32_e32 v2, v2, v12
	v_mov_b32_e32 v3, v135
	s_mov_b64 s[4:5], 0x100080
	v_lshl_add_u64 v[138:139], v[2:3], 0, s[4:5]
	v_lshlrev_b32_e32 v2, 7, v10
	v_and_b32_e32 v2, 0xc0000, v2
	s_waitcnt vmcnt(6)
	v_or3_b32 v2, v11, v2, v4
	v_add3_u32 v2, v2, v1, v12
	s_add_i32 s75, 0, 0x10000
	s_add_i32 s76, 0, 0x14000
	s_add_i32 s74, s74, 0x20000
	v_lshl_add_u64 v[140:141], v[2:3], 0, s[4:5]
	v_mov_b64_e32 v[142:143], 0xb00
	v_mov_b64_e32 v[144:145], 0xaff
	v_add_u32_e32 v175, s75, v174
	v_add_u32_e32 v176, s76, v174
	v_add_u32_e32 v177, 0, v5
	s_add_i32 s77, 0, 0x22004
	s_add_i32 s78, 0, 0x2200c
	s_add_i32 s79, 0, 0x22014
	s_add_i32 s80, 0, 0x2201c
	s_mov_b32 s81, 0xc3e00000
	s_movk_i32 s82, 0x1600
	v_mov_b32_e32 v178, 0x400
	v_mov_b32_e32 v179, 0x800
	v_mov_b32_e32 v180, 0xc00
	v_mov_b32_e32 v181, 0x1400
	v_mov_b32_e32 v182, 0x1800
	v_mov_b32_e32 v183, 0x1c00
	v_mov_b32_e32 v184, 0x43e00000
	s_barrier
	s_branch .LBB0_912

; #define PG8_STAGE(bufoff, gbase, voff) do { _Pragma("unroll") for (int _i = 0; _i < 2; ++_i) \
;         __builtin_amdgcn_global_load_lds((const unsigned*)((const char*)(gbase) + (voff)[_i]), (PG8_LAS unsigned*)(lds + (bufoff) + ldsw + _i * 8192), 16, 0, 0); } while (0)
; #define PG8_LDA(dst, b, h) do { _Pragma("unroll") for (int m = 0; m < 4; ++m) _Pragma("unroll") for (int k = 0; k < 2; ++k) dst[m][k] = *(const PG8_LAS bf16x8*)(lds + PG8_SA(b, h) + aoff + m * 2048 + k * 1024); } while (0)
; #define PG8_LDB(dst, b, h) do { _Pragma("unroll") for (int n = 0; n < 2; ++n) _Pragma("unroll") for (int k = 0; k < 2; ++k) dst[n][k] = *(const PG8_LAS bf16x8*)(lds + PG8_SB(b, h) + boff + n * 2048 + k * 1024); } while (0)
; #define PG8_WAIT_V(n) asm volatile("s_waitcnt vmcnt(" #n ")" ::: "memory")
; #define PG8_WAIT_L(n) asm volatile("s_waitcnt lgkmcnt(" #n ")" ::: "memory")
; #define PG8_BAR __builtin_amdgcn_s_barrier()
; #define PG8_SCHED __builtin_amdgcn_sched_barrier(0)
; template <class Epi, class Sched, bool ALIGN_EPI = false, bool SP2 = false, bool F8 = false>
; __device__ __forceinline__ void gemm_phase(PG8_LAS unsigned char* lds, const Gemm g, const Sched& S, const Epi& E) {
;     ...
;             PG8_LDB(B0, 0, 0); PG8_LDB(B1, 0, 1); PG8_SCHED; PG8_LDA(At, 0, 0); PG8_STAGE(PG8_SA(1, 1), a1 + hstepA, voffA);
;             PG8_WAIT_V(8); PG8_WAIT_L(0); PG8_BAR; PG8_MMA(0, 0, At, B0); PG8_MMA(0, 1, At, B1); PG8_BAR; PG8_SCHED;
;             PG8_LDA(At, 0, 1); PG8_STAGE(PG8_SB(0, 0), b2, voffB); PG8_STAGE(PG8_SB(0, 1), b2 + hstep, voffB); PG8_STAGE(PG8_SA(0, 0), a2, voffA);
;             PG8_WAIT_V(8); PG8_WAIT_L(0); PG8_BAR; PG8_MMA(1, 0, At, B0); PG8_MMA(1, 1, At, B1); PG8_BAR; PG8_SCHED;
.LBB0_917:
	ds_read_b128 v[146:149], v175
	ds_read_b128 v[150:153], v175 offset:1024
	ds_read_b128 v[154:157], v175 offset:2048
	ds_read_b128 v[158:161], v175 offset:3072
	ds_read_b128 v[162:165], v176
	ds_read_b128 v[166:169], v176 offset:1024
	ds_read_b128 v[186:189], v176 offset:2048
	ds_read_b128 v[190:193], v176 offset:3072
	s_add_u32 s6, s56, 0x100
	s_addc_u32 s7, s57, 0
	s_cmp_eq_u32 s29, 28
	s_cselect_b32 s61, s53, s7
	s_cselect_b32 s60, s52, s6
	s_cselect_b32 s59, s15, s28
	s_cselect_b32 s58, s26, s27
	v_lshl_add_u64 v[170:171], s[56:57], 0, v[138:139]
	s_add_i32 m0, s65, 0xc000
	ds_read_b128 v[194:197], v177
	ds_read_b128 v[198:201], v177 offset:1024
	ds_read_b128 v[202:205], v177 offset:2048
	ds_read_b128 v[206:209], v177 offset:3072
	ds_read_b128 v[210:213], v177 offset:4096
	ds_read_b128 v[218:221], v177 offset:5120
	ds_read_b128 v[222:225], v177 offset:6144
	ds_read_b128 v[226:229], v177 offset:7168
	global_load_lds_dwordx4 v[170:171], off
	v_lshl_add_u64 v[170:171], s[56:57], 0, v[140:141]
	s_add_i32 m0, s65, 0xe000
	s_nop 0
	global_load_lds_dwordx4 v[170:171], off
	s_waitcnt vmcnt(8)
	s_waitcnt lgkmcnt(0)
	s_barrier
	s_setprio 1
	s_waitcnt lgkmcnt(0)
	v_mfma_f32_16x16x32_bf16 v[126:129], v[146:149], v[194:197], v[126:129]
	v_mfma_f32_16x16x32_bf16 v[122:125], v[154:157], v[194:197], v[122:125]
	v_mfma_f32_16x16x32_bf16 v[118:121], v[146:149], v[202:205], v[118:121]
	v_mfma_f32_16x16x32_bf16 v[114:117], v[154:157], v[202:205], v[114:117]
	v_mfma_f32_16x16x32_bf16 v[110:113], v[146:149], v[210:213], v[110:113]
	v_mfma_f32_16x16x32_bf16 v[102:105], v[154:157], v[210:213], v[102:105]
	v_mfma_f32_16x16x32_bf16 v[94:97], v[146:149], v[222:225], v[94:97]
	v_mfma_f32_16x16x32_bf16 v[86:89], v[154:157], v[222:225], v[86:89]
	v_mfma_f32_16x16x32_bf16 v[126:129], v[150:153], v[198:201], v[126:129]
	v_mfma_f32_16x16x32_bf16 v[122:125], v[158:161], v[198:201], v[122:125]
	v_mfma_f32_16x16x32_bf16 v[118:121], v[150:153], v[206:209], v[118:121]
	v_mfma_f32_16x16x32_bf16 v[114:117], v[158:161], v[206:209], v[114:117]
	v_mfma_f32_16x16x32_bf16 v[110:113], v[150:153], v[218:221], v[110:113]
	v_mfma_f32_16x16x32_bf16 v[102:105], v[158:161], v[218:221], v[102:105]
	v_mfma_f32_16x16x32_bf16 v[94:97], v[150:153], v[226:229], v[94:97]
	v_mfma_f32_16x16x32_bf16 v[86:89], v[158:161], v[226:229], v[86:89]
	s_setprio 0
	s_setprio 1
	v_mfma_f32_16x16x32_bf16 v[106:109], v[162:165], v[194:197], v[106:109]
	v_mfma_f32_16x16x32_bf16 v[98:101], v[186:189], v[194:197], v[98:101]
	v_mfma_f32_16x16x32_bf16 v[90:93], v[162:165], v[202:205], v[90:93]
	v_mfma_f32_16x16x32_bf16 v[82:85], v[186:189], v[202:205], v[82:85]
	v_mfma_f32_16x16x32_bf16 v[78:81], v[162:165], v[210:213], v[78:81]
	v_mfma_f32_16x16x32_bf16 v[74:77], v[186:189], v[210:213], v[74:77]
	v_mfma_f32_16x16x32_bf16 v[70:73], v[162:165], v[222:225], v[70:73]
	v_mfma_f32_16x16x32_bf16 v[66:69], v[186:189], v[222:225], v[66:69]
	v_mfma_f32_16x16x32_bf16 v[106:109], v[166:169], v[198:201], v[106:109]
	v_mfma_f32_16x16x32_bf16 v[98:101], v[190:193], v[198:201], v[98:101]
	v_mfma_f32_16x16x32_bf16 v[90:93], v[166:169], v[206:209], v[90:93]
	v_mfma_f32_16x16x32_bf16 v[82:85], v[190:193], v[206:209], v[82:85]
	v_mfma_f32_16x16x32_bf16 v[78:81], v[166:169], v[218:221], v[78:81]
	v_mfma_f32_16x16x32_bf16 v[74:77], v[190:193], v[218:221], v[74:77]
	v_mfma_f32_16x16x32_bf16 v[70:73], v[166:169], v[226:229], v[70:73]
	v_mfma_f32_16x16x32_bf16 v[66:69], v[190:193], v[226:229], v[66:69]
	s_setprio 0
	s_barrier
	s_add_i32 s24, s75, s62
	v_lshl_add_u64 v[170:171], s[58:59], 0, v[134:135]
	s_mov_b32 m0, s24
	ds_read_b128 v[194:197], v177 offset:16384
	ds_read_b128 v[198:201], v177 offset:17408
	ds_read_b128 v[202:205], v177 offset:18432
	ds_read_b128 v[206:209], v177 offset:19456
	ds_read_b128 v[210:213], v177 offset:20480
	ds_read_b128 v[218:221], v177 offset:21504
	ds_read_b128 v[222:225], v177 offset:22528
	ds_read_b128 v[226:229], v177 offset:23552
	global_load_lds_dwordx4 v[170:171], off
	s_add_i32 m0, s24, 0x2000
	s_add_u32 s24, s58, 0x80000
	v_lshl_add_u64 v[214:215], s[58:59], 0, v[130:131]
	s_addc_u32 s25, s59, 0
	s_add_i32 s33, s76, s62
	global_load_lds_dwordx4 v[214:215], off
	v_lshl_add_u64 v[230:231], s[24:25], 0, v[134:135]
	s_mov_b32 m0, s33
	v_lshl_add_u64 v[232:233], s[60:61], 0, v[132:133]
	global_load_lds_dwordx4 v[230:231], off
	v_lshl_add_u64 v[230:231], s[24:25], 0, v[130:131]
	s_add_i32 m0, s33, 0x2000
	s_nop 0
	global_load_lds_dwordx4 v[230:231], off
	v_lshl_add_u64 v[230:231], s[60:61], 0, v[136:137]
	s_mov_b32 m0, s65
	s_nop 0
	global_load_lds_dwordx4 v[230:231], off
	s_mov_b32 m0, s66
	s_nop 0
	global_load_lds_dwordx4 v[232:233], off
	s_waitcnt vmcnt(8)
	s_waitcnt lgkmcnt(0)
	s_barrier
; #define PG8_STAGE(bufoff, gbase, voff) do { _Pragma("unroll") for (int _i = 0; _i < 2; ++_i) \
;         __builtin_amdgcn_global_load_lds((const unsigned*)((const char*)(gbase) + (voff)[_i]), (PG8_LAS unsigned*)(lds + (bufoff) + ldsw + _i * 8192), 16, 0, 0); } while (0)
; #define PG8_LDA(dst, b, h) do { _Pragma("unroll") for (int m = 0; m < 4; ++m) _Pragma("unroll") for (int k = 0; k < 2; ++k) dst[m][k] = *(const PG8_LAS bf16x8*)(lds + PG8_SA(b, h) + aoff + m * 2048 + k * 1024); } while (0)
; #define PG8_LDB(dst, b, h) do { _Pragma("unroll") for (int n = 0; n < 2; ++n) _Pragma("unroll") for (int k = 0; k < 2; ++k) dst[n][k] = *(const PG8_LAS bf16x8*)(lds + PG8_SB(b, h) + boff + n * 2048 + k * 1024); } while (0)
; #define PG8_WAIT_V(n) asm volatile("s_waitcnt vmcnt(" #n ")" ::: "memory")
; #define PG8_WAIT_L(n) asm volatile("s_waitcnt lgkmcnt(" #n ")" ::: "memory")
; #define PG8_BAR __builtin_amdgcn_s_barrier()
; #define PG8_SCHED __builtin_amdgcn_sched_barrier(0)
; template <class Epi, class Sched, bool ALIGN_EPI = false, bool SP2 = false, bool F8 = false>
; __device__ __forceinline__ void gemm_phase(PG8_LAS unsigned char* lds, const Gemm g, const Sched& S, const Epi& E) {
;     ...
;             PG8_WAIT_V(8); PG8_WAIT_L(0); PG8_BAR; PG8_MMA(1, 0, At, B0); PG8_MMA(1, 1, At, B1); PG8_BAR; PG8_SCHED;
;             PG8_LDB(B0, 1, 0); PG8_LDB(B1, 1, 1); PG8_SCHED; PG8_LDA(At, 1, 0); PG8_STAGE(PG8_SA(0, 1), a2 + hstepA, voffA);
;             PG8_WAIT_V(8); PG8_WAIT_L(0); PG8_BAR; PG8_MMA(0, 0, At, B0); PG8_MMA(0, 1, At, B1); PG8_BAR; PG8_SCHED;
	s_setprio 1
	s_waitcnt lgkmcnt(0)
	v_mfma_f32_16x16x32_bf16 v[62:65], v[146:149], v[194:197], v[62:65]
	v_mfma_f32_16x16x32_bf16 v[58:61], v[154:157], v[194:197], v[58:61]
	v_mfma_f32_16x16x32_bf16 v[54:57], v[146:149], v[202:205], v[54:57]
	v_mfma_f32_16x16x32_bf16 v[50:53], v[154:157], v[202:205], v[50:53]
	v_mfma_f32_16x16x32_bf16 v[38:41], v[146:149], v[210:213], v[38:41]
	v_mfma_f32_16x16x32_bf16 v[34:37], v[154:157], v[210:213], v[34:37]
	v_mfma_f32_16x16x32_bf16 v[22:25], v[146:149], v[222:225], v[22:25]
	v_mfma_f32_16x16x32_bf16 v[18:21], v[154:157], v[222:225], v[18:21]
	v_mfma_f32_16x16x32_bf16 v[62:65], v[150:153], v[198:201], v[62:65]
	v_mfma_f32_16x16x32_bf16 v[58:61], v[158:161], v[198:201], v[58:61]
	v_mfma_f32_16x16x32_bf16 v[54:57], v[150:153], v[206:209], v[54:57]
	v_mfma_f32_16x16x32_bf16 v[50:53], v[158:161], v[206:209], v[50:53]
	v_mfma_f32_16x16x32_bf16 v[38:41], v[150:153], v[218:221], v[38:41]
	v_mfma_f32_16x16x32_bf16 v[34:37], v[158:161], v[218:221], v[34:37]
	v_mfma_f32_16x16x32_bf16 v[22:25], v[150:153], v[226:229], v[22:25]
	v_mfma_f32_16x16x32_bf16 v[18:21], v[158:161], v[226:229], v[18:21]
	s_setprio 0
	s_setprio 1
	v_mfma_f32_16x16x32_bf16 v[46:49], v[162:165], v[194:197], v[46:49]
	v_mfma_f32_16x16x32_bf16 v[42:45], v[186:189], v[194:197], v[42:45]
	v_mfma_f32_16x16x32_bf16 v[30:33], v[162:165], v[202:205], v[30:33]
	v_mfma_f32_16x16x32_bf16 v[26:29], v[186:189], v[202:205], v[26:29]
	v_mfma_f32_16x16x32_bf16 v[14:17], v[162:165], v[210:213], v[14:17]
	v_mfma_f32_16x16x32_bf16 v[10:13], v[186:189], v[210:213], v[10:13]
	v_mfma_f32_16x16x32_bf16 v[6:9], v[162:165], v[222:225], v[6:9]
	v_mfma_f32_16x16x32_bf16 v[2:5], v[186:189], v[222:225], v[2:5]
	v_mfma_f32_16x16x32_bf16 v[46:49], v[166:169], v[198:201], v[46:49]
	v_mfma_f32_16x16x32_bf16 v[42:45], v[190:193], v[198:201], v[42:45]
	v_mfma_f32_16x16x32_bf16 v[30:33], v[166:169], v[206:209], v[30:33]
	v_mfma_f32_16x16x32_bf16 v[26:29], v[190:193], v[206:209], v[26:29]
	v_mfma_f32_16x16x32_bf16 v[14:17], v[166:169], v[218:221], v[14:17]
	v_mfma_f32_16x16x32_bf16 v[10:13], v[190:193], v[218:221], v[10:13]
	v_mfma_f32_16x16x32_bf16 v[6:9], v[166:169], v[226:229], v[6:9]
	v_mfma_f32_16x16x32_bf16 v[2:5], v[190:193], v[226:229], v[2:5]
	s_setprio 0
	s_barrier
	s_add_i32 s33, 0, 0x18000
	s_add_i32 s36, 0, 0x1c000
	v_add_u32_e32 v158, s33, v174
	v_add_u32_e32 v185, s36, v174
	ds_read_b128 v[146:149], v158
	ds_read_b128 v[150:153], v158 offset:1024
	ds_read_b128 v[154:157], v158 offset:2048
	ds_read_b128 v[158:161], v158 offset:3072
	ds_read_b128 v[162:165], v185
	ds_read_b128 v[166:169], v185 offset:1024
	ds_read_b128 v[186:189], v185 offset:2048
	ds_read_b128 v[190:193], v185 offset:3072
	s_add_u32 s24, s60, 0x100000
	s_addc_u32 s25, s61, 0
	s_mov_b32 m0, s67
	v_lshl_add_u64 v[234:235], s[24:25], 0, v[136:137]
	ds_read_b128 v[194:197], v177 offset:32768
	ds_read_b128 v[198:201], v177 offset:33792
	ds_read_b128 v[202:205], v177 offset:34816
	ds_read_b128 v[206:209], v177 offset:35840
	ds_read_b128 v[210:213], v177 offset:36864
	ds_read_b128 v[218:221], v177 offset:37888
	ds_read_b128 v[222:225], v177 offset:38912
	ds_read_b128 v[226:229], v177 offset:39936
	global_load_lds_dwordx4 v[234:235], off
	v_lshl_add_u64 v[234:235], s[24:25], 0, v[132:133]
	s_mov_b32 m0, s68
	s_nop 0
	global_load_lds_dwordx4 v[234:235], off
	s_waitcnt vmcnt(8)
	s_waitcnt lgkmcnt(0)
	s_barrier
	s_setprio 1
	s_waitcnt lgkmcnt(0)
	v_mfma_f32_16x16x32_bf16 v[126:129], v[146:149], v[194:197], v[126:129]
	v_mfma_f32_16x16x32_bf16 v[122:125], v[154:157], v[194:197], v[122:125]
	v_mfma_f32_16x16x32_bf16 v[118:121], v[146:149], v[202:205], v[118:121]
	v_mfma_f32_16x16x32_bf16 v[114:117], v[154:157], v[202:205], v[114:117]
	v_mfma_f32_16x16x32_bf16 v[110:113], v[146:149], v[210:213], v[110:113]
	v_mfma_f32_16x16x32_bf16 v[102:105], v[154:157], v[210:213], v[102:105]
	v_mfma_f32_16x16x32_bf16 v[94:97], v[146:149], v[222:225], v[94:97]
	v_mfma_f32_16x16x32_bf16 v[86:89], v[154:157], v[222:225], v[86:89]
	v_mfma_f32_16x16x32_bf16 v[126:129], v[150:153], v[198:201], v[126:129]
	v_mfma_f32_16x16x32_bf16 v[122:125], v[158:161], v[198:201], v[122:125]
	v_mfma_f32_16x16x32_bf16 v[118:121], v[150:153], v[206:209], v[118:121]
	v_mfma_f32_16x16x32_bf16 v[114:117], v[158:161], v[206:209], v[114:117]
	v_mfma_f32_16x16x32_bf16 v[110:113], v[150:153], v[218:221], v[110:113]
	v_mfma_f32_16x16x32_bf16 v[102:105], v[158:161], v[218:221], v[102:105]
	v_mfma_f32_16x16x32_bf16 v[94:97], v[150:153], v[226:229], v[94:97]
	v_mfma_f32_16x16x32_bf16 v[86:89], v[158:161], v[226:229], v[86:89]
	s_setprio 0
	s_setprio 1
	v_mfma_f32_16x16x32_bf16 v[106:109], v[162:165], v[194:197], v[106:109]
	v_mfma_f32_16x16x32_bf16 v[98:101], v[186:189], v[194:197], v[98:101]
	v_mfma_f32_16x16x32_bf16 v[90:93], v[162:165], v[202:205], v[90:93]
	v_mfma_f32_16x16x32_bf16 v[82:85], v[186:189], v[202:205], v[82:85]
	v_mfma_f32_16x16x32_bf16 v[78:81], v[162:165], v[210:213], v[78:81]
	v_mfma_f32_16x16x32_bf16 v[74:77], v[186:189], v[210:213], v[74:77]
	v_mfma_f32_16x16x32_bf16 v[70:73], v[162:165], v[222:225], v[70:73]
	v_mfma_f32_16x16x32_bf16 v[66:69], v[186:189], v[222:225], v[66:69]
	v_mfma_f32_16x16x32_bf16 v[106:109], v[166:169], v[198:201], v[106:109]
	v_mfma_f32_16x16x32_bf16 v[98:101], v[190:193], v[198:201], v[98:101]
	v_mfma_f32_16x16x32_bf16 v[90:93], v[166:169], v[206:209], v[90:93]
	v_mfma_f32_16x16x32_bf16 v[82:85], v[190:193], v[206:209], v[82:85]
	v_mfma_f32_16x16x32_bf16 v[78:81], v[166:169], v[218:221], v[78:81]
	v_mfma_f32_16x16x32_bf16 v[74:77], v[190:193], v[218:221], v[74:77]
	v_mfma_f32_16x16x32_bf16 v[70:73], v[166:169], v[226:229], v[70:73]
	v_mfma_f32_16x16x32_bf16 v[66:69], v[190:193], v[226:229], v[66:69]
	s_setprio 0
	s_barrier
; #define PG8_STAGE(bufoff, gbase, voff) do { _Pragma("unroll") for (int _i = 0; _i < 2; ++_i) \
;         __builtin_amdgcn_global_load_lds((const unsigned*)((const char*)(gbase) + (voff)[_i]), (PG8_LAS unsigned*)(lds + (bufoff) + ldsw + _i * 8192), 16, 0, 0); } while (0)
; #define PG8_LDA(dst, b, h) do { _Pragma("unroll") for (int m = 0; m < 4; ++m) _Pragma("unroll") for (int k = 0; k < 2; ++k) dst[m][k] = *(const PG8_LAS bf16x8*)(lds + PG8_SA(b, h) + aoff + m * 2048 + k * 1024); } while (0)
; #define PG8_WAIT_V(n) asm volatile("s_waitcnt vmcnt(" #n ")" ::: "memory")
; #define PG8_WAIT_L(n) asm volatile("s_waitcnt lgkmcnt(" #n ")" ::: "memory")
; #define PG8_BAR __builtin_amdgcn_s_barrier()
; #define PG8_SCHED __builtin_amdgcn_sched_barrier(0)
;     __device__ __forceinline__ void operator()(f32x4 (&acc)[2][2][4][2], const Unit& u, int wr, int wc, int fr, int fq) const {
;     ...
;         const int b = u.pm >> 5, cp = u.pm & 31;
;         const int chl = 32 * wc + 8 * fq, ch = 128 * u.pn + chl;
;         const size_t tok00 = (size_t)b * 8192 + 2 * cp + wr;
;         {
;             const float* bp = bias + (size_t)b * bias_bstride + 256 * u.pn + chl;
;             int slot = 0;
; #pragma unroll
;             for (int j = 1; j < 8; ++j) if (pml[j] == u.pm) slot = j;
;             const f32x4 ba0 = *(const f32x4*)(bp), ba1 = *(const f32x4*)(bp + 4), bb0 = *(const f32x4*)(bp + 128), bb1 = *(const f32x4*)(bp + 132);
; #pragma unroll
;             for (int ai = 0; ai < 2; ++ai)
; #pragma unroll
;                 for (int m = 0; m < 4; ++m) { const int rl = ai * HALF + wr * 64 + m * 16 + fr; const float rsv = rs[slot * 256 + rl];
; template <class Epi, class Sched, bool ALIGN_EPI = false, bool SP2 = false, bool F8 = false>
; __device__ __forceinline__ void gemm_phase(PG8_LAS unsigned char* lds, const Gemm g, const Sched& S, const Epi& E) {
;     ...
;             PG8_WAIT_V(8); PG8_WAIT_L(0); PG8_BAR; PG8_MMA(0, 0, At, B0); PG8_MMA(0, 1, At, B1); PG8_BAR; PG8_SCHED;
;             PG8_LDA(At, 1, 1); PG8_STAGE(PG8_SB(1, 0), b3, voffB); PG8_STAGE(PG8_SB(1, 1), b3 + hstep, voffB); PG8_STAGE(PG8_SA(1, 0), a3, voffA);
;             PG8_WAIT_V(8); PG8_WAIT_L(0); PG8_BAR; PG8_MMA(1, 0, At, B0); PG8_MMA(1, 1, At, B1); PG8_BAR; PG8_SCHED;
	s_add_i32 s24, s33, s62
	v_lshl_add_u64 v[170:171], v[170:171], 0, s[40:41]
	s_mov_b32 m0, s24
	ds_read_b128 v[194:197], v177 offset:49152
	ds_read_b128 v[198:201], v177 offset:50176
	ds_read_b128 v[202:205], v177 offset:51200
	ds_read_b128 v[206:209], v177 offset:52224
	ds_read_b128 v[210:213], v177 offset:53248
	ds_read_b128 v[218:221], v177 offset:54272
	ds_read_b128 v[222:225], v177 offset:55296
	ds_read_b128 v[226:229], v177 offset:56320
	global_load_lds_dwordx4 v[170:171], off
	s_add_i32 m0, s24, 0x2000
	s_add_u32 s24, s58, 0x80080
	v_lshl_add_u64 v[170:171], v[214:215], 0, s[40:41]
	s_addc_u32 s25, s59, 0
	s_add_i32 s33, s36, s62
	global_load_lds_dwordx4 v[170:171], off
	v_lshl_add_u64 v[170:171], s[24:25], 0, v[134:135]
	s_mov_b32 m0, s33
	s_nop 0
	global_load_lds_dwordx4 v[170:171], off
	v_lshl_add_u64 v[170:171], s[24:25], 0, v[130:131]
	s_add_i32 m0, s33, 0x2000
	s_nop 0
	global_load_lds_dwordx4 v[170:171], off
	v_lshl_add_u64 v[170:171], v[230:231], 0, s[40:41]
	s_mov_b32 m0, s71
	s_nop 0
	global_load_lds_dwordx4 v[170:171], off
	v_lshl_add_u64 v[170:171], v[232:233], 0, s[40:41]
	s_mov_b32 m0, s72
	s_nop 0
	global_load_lds_dwordx4 v[170:171], off
	s_waitcnt vmcnt(8)
	s_waitcnt lgkmcnt(0)
	s_barrier
	s_setprio 1
	s_waitcnt lgkmcnt(0)
	v_mfma_f32_16x16x32_bf16 v[62:65], v[146:149], v[194:197], v[62:65]
	v_mfma_f32_16x16x32_bf16 v[58:61], v[154:157], v[194:197], v[58:61]
	v_mfma_f32_16x16x32_bf16 v[54:57], v[146:149], v[202:205], v[54:57]
	v_mfma_f32_16x16x32_bf16 v[50:53], v[154:157], v[202:205], v[50:53]
	v_mfma_f32_16x16x32_bf16 v[38:41], v[146:149], v[210:213], v[38:41]
	v_mfma_f32_16x16x32_bf16 v[34:37], v[154:157], v[210:213], v[34:37]
	v_mfma_f32_16x16x32_bf16 v[22:25], v[146:149], v[222:225], v[22:25]
	v_mfma_f32_16x16x32_bf16 v[18:21], v[154:157], v[222:225], v[18:21]
	v_mfma_f32_16x16x32_bf16 v[62:65], v[150:153], v[198:201], v[62:65]
	v_mfma_f32_16x16x32_bf16 v[58:61], v[158:161], v[198:201], v[58:61]
	v_mfma_f32_16x16x32_bf16 v[54:57], v[150:153], v[206:209], v[54:57]
	v_mfma_f32_16x16x32_bf16 v[50:53], v[158:161], v[206:209], v[50:53]
	v_mfma_f32_16x16x32_bf16 v[38:41], v[150:153], v[218:221], v[38:41]
	v_mfma_f32_16x16x32_bf16 v[34:37], v[158:161], v[218:221], v[34:37]
	v_mfma_f32_16x16x32_bf16 v[22:25], v[150:153], v[226:229], v[22:25]
	v_mfma_f32_16x16x32_bf16 v[18:21], v[158:161], v[226:229], v[18:21]
	s_setprio 0
	s_setprio 1
	v_mfma_f32_16x16x32_bf16 v[46:49], v[162:165], v[194:197], v[46:49]
	v_mfma_f32_16x16x32_bf16 v[42:45], v[186:189], v[194:197], v[42:45]
	v_mfma_f32_16x16x32_bf16 v[30:33], v[162:165], v[202:205], v[30:33]
	v_mfma_f32_16x16x32_bf16 v[26:29], v[186:189], v[202:205], v[26:29]
	v_mfma_f32_16x16x32_bf16 v[14:17], v[162:165], v[210:213], v[14:17]
	v_mfma_f32_16x16x32_bf16 v[10:13], v[186:189], v[210:213], v[10:13]
	v_mfma_f32_16x16x32_bf16 v[6:9], v[162:165], v[222:225], v[6:9]
	v_mfma_f32_16x16x32_bf16 v[2:5], v[186:189], v[222:225], v[2:5]
	v_mfma_f32_16x16x32_bf16 v[46:49], v[166:169], v[198:201], v[46:49]
	v_mfma_f32_16x16x32_bf16 v[42:45], v[190:193], v[198:201], v[42:45]
	v_mfma_f32_16x16x32_bf16 v[30:33], v[166:169], v[206:209], v[30:33]
	v_mfma_f32_16x16x32_bf16 v[26:29], v[190:193], v[206:209], v[26:29]
	v_mfma_f32_16x16x32_bf16 v[14:17], v[166:169], v[218:221], v[14:17]
	v_mfma_f32_16x16x32_bf16 v[10:13], v[190:193], v[218:221], v[10:13]
	v_mfma_f32_16x16x32_bf16 v[6:9], v[166:169], v[226:229], v[6:9]
	v_mfma_f32_16x16x32_bf16 v[2:5], v[190:193], v[226:229], v[2:5]
	s_setprio 0
	s_barrier
	s_add_i32 s29, s29, 2
	s_add_u32 s27, s27, 0x100
	s_addc_u32 s28, s28, 0
	s_cmp_gt_u32 s29, 29
	s_mov_b64 s[56:57], s[6:7]
	s_cbranch_scc0 .LBB0_917
	s_and_b64 vcc, exec, s[44:45]
	s_cbranch_vccz .LBB0_920
	s_barrier
.LBB0_920:
	s_ashr_i32 s56, s84, 5
	s_lshl_b32 s6, s14, 10
	s_mul_i32 s24, s56, 0xb000
	s_add_i32 s24, s24, s6
	s_add_u32 s6, s3, s24
	s_addc_u32 s7, s21, 0
	s_lshl_b32 s15, s14, 9
	s_lshl_b32 s25, s70, 2
	v_lshlrev_b32_e32 v146, 5, v173
	v_add_u32_e32 v146, s25, v146
	v_add_u32_e32 v147, s15, v146
	global_load_dwordx4 v[156:159], v146, s[6:7]
	global_load_dwordx4 v[160:163], v146, s[6:7] offset:16
	global_load_dwordx4 v[164:167], v146, s[6:7] offset:512
	global_load_dwordx4 v[168:171], v146, s[6:7] offset:528
	global_load_dwordx4 v[188:191], v147, s[8:9]
	global_load_dwordx4 v[192:195], v147, s[8:9] offset:16
	global_load_dwordx4 v[196:199], v147, s[46:47]
	global_load_dwordx4 v[200:203], v147, s[46:47] offset:16
	global_load_dwordx4 v[204:207], v147, s[48:49]
	global_load_dwordx4 v[208:211], v147, s[48:49] offset:16
	global_load_dwordx4 v[212:215], v147, s[10:11]
	global_load_dwordx4 v[218:221], v147, s[10:11] offset:16
	v_mov_b32_e32 v222, s77
	ds_read2_b32 v[222:223], v222 offset1:1
	v_mov_b32_e32 v224, s78
	v_mov_b32_e32 v226, s79
	v_mov_b32_e32 v228, s80
	ds_read2_b32 v[224:225], v224 offset1:1
	ds_read2_b32 v[226:227], v226 offset1:1
	ds_read_b32 v228, v228
	s_lshl_b32 s24, s84, 1
	s_and_b32 s24, s24, 62
	s_lshl_b32 s25, s56, 13
	s_add_i32 s24, s24, s25
	s_mul_i32 s24, s24, 0x1600
	s_lshl_b32 s25, s14, 7
	s_add_i32 s24, s24, s25
	s_add_u32 s28, s38, s24
	s_addc_u32 s29, s39, 0
	v_and_b32_e32 v186, 1, v173
	v_mul_u32_u24_e32 v185, 0x2c0000, v172
	v_mul_u32_u24_e32 v186, 0x57ff8, v186
	v_lshl_add_u32 v187, v173, 3, s70
	v_add3_u32 v185, v185, v186, v187
	s_mul_i32 s25, s23, 0x1600
	v_add_u32_e32 v185, s25, v185
	v_lshrrev_b32_e32 v230, 3, v172
	v_and_b32_e32 v232, 7, v172
	v_lshlrev_b32_e32 v232, 5, v232
	v_lshl_or_b32 v230, v230, 9, v232
	s_mov_b32 s26, 1.0
	s_mov_b32 s27, 1.0
	s_waitcnt lgkmcnt(0)
;     __device__ __forceinline__ void operator()(f32x4 (&acc)[2][2][4][2], const Unit& u, int wr, int wc, int fr, int fq) const {
;     ...
;             for (int j = 1; j < 8; ++j) if (pml[j] == u.pm) slot = j;
;             const f32x4 ba0 = *(const f32x4*)(bp), ba1 = *(const f32x4*)(bp + 4), bb0 = *(const f32x4*)(bp + 128), bb1 = *(const f32x4*)(bp + 132);
; #pragma unroll
;             for (int ai = 0; ai < 2; ++ai)
; #pragma unroll
;                 for (int m = 0; m < 4; ++m) { const int rl = ai * HALF + wr * 64 + m * 16 + fr; const float rsv = rs[slot * 256 + rl];
;                     acc[ai][0][m][0] = acc[ai][0][m][0] * rsv + ba0; acc[ai][0][m][1] = acc[ai][0][m][1] * rsv + ba1; acc[ai][1][m][0] = acc[ai][1][m][0] * rsv + bb0; acc[ai][1][m][1] = acc[ai][1][m][1] * rsv + bb1; }
	v_cmp_eq_u32_e32 vcc, s84, v222
	s_nop 1
	v_cndmask_b32_e32 v231, 0, v178, vcc
	v_cmp_ne_u32_e32 vcc, s84, v223
	s_nop 1
	v_cndmask_b32_e32 v231, v179, v231, vcc
	v_cmp_ne_u32_e32 vcc, s84, v224
	s_nop 1
	v_cndmask_b32_e32 v231, v180, v231, vcc
	v_cmp_ne_u32_e32 vcc, s84, v225
	s_nop 1
	v_cndmask_b32_e32 v231, v1, v231, vcc
	v_cmp_ne_u32_e32 vcc, s84, v226
	s_nop 1
	v_cndmask_b32_e32 v231, v181, v231, vcc
	v_cmp_ne_u32_e32 vcc, s84, v227
	s_nop 1
	v_cndmask_b32_e32 v231, v182, v231, vcc
	v_cmp_ne_u32_e32 vcc, s84, v228
	s_nop 1
	v_cndmask_b32_e32 v231, v183, v231, vcc
	v_add3_u32 v230, v230, v231, s74
	ds_read_b128 v[148:151], v230
	ds_read_b128 v[152:155], v230 offset:16
	s_waitcnt lgkmcnt(0)
	s_waitcnt vmcnt(8)
	v_pk_fma_f32 v[126:127], v[126:127], v[148:149], v[156:157] op_sel_hi:[1,0,1]
	v_pk_fma_f32 v[128:129], v[128:129], v[148:149], v[158:159] op_sel_hi:[1,0,1]
	v_pk_fma_f32 v[122:123], v[122:123], v[148:149], v[160:161] op_sel_hi:[1,0,1]
	v_pk_fma_f32 v[124:125], v[124:125], v[148:149], v[162:163] op_sel_hi:[1,0,1]
	v_pk_fma_f32 v[118:119], v[118:119], v[148:149], v[156:157] op_sel:[0,1,0] op_sel_hi:[1,1,1]
	v_pk_fma_f32 v[120:121], v[120:121], v[148:149], v[158:159] op_sel:[0,1,0] op_sel_hi:[1,1,1]
	v_pk_fma_f32 v[114:115], v[114:115], v[148:149], v[160:161] op_sel:[0,1,0] op_sel_hi:[1,1,1]
	v_pk_fma_f32 v[116:117], v[116:117], v[148:149], v[162:163] op_sel:[0,1,0] op_sel_hi:[1,1,1]
	v_pk_fma_f32 v[110:111], v[110:111], v[150:151], v[156:157] op_sel_hi:[1,0,1]
	v_pk_fma_f32 v[112:113], v[112:113], v[150:151], v[158:159] op_sel_hi:[1,0,1]
	v_pk_fma_f32 v[102:103], v[102:103], v[150:151], v[160:161] op_sel_hi:[1,0,1]
	v_pk_fma_f32 v[104:105], v[104:105], v[150:151], v[162:163] op_sel_hi:[1,0,1]
	v_pk_fma_f32 v[94:95], v[94:95], v[150:151], v[156:157] op_sel:[0,1,0] op_sel_hi:[1,1,1]
	v_pk_fma_f32 v[96:97], v[96:97], v[150:151], v[158:159] op_sel:[0,1,0] op_sel_hi:[1,1,1]
	v_pk_fma_f32 v[86:87], v[86:87], v[150:151], v[160:161] op_sel:[0,1,0] op_sel_hi:[1,1,1]
	v_pk_fma_f32 v[88:89], v[88:89], v[150:151], v[162:163] op_sel:[0,1,0] op_sel_hi:[1,1,1]
	v_pk_fma_f32 v[62:63], v[62:63], v[152:153], v[156:157] op_sel_hi:[1,0,1]
	v_pk_fma_f32 v[64:65], v[64:65], v[152:153], v[158:159] op_sel_hi:[1,0,1]
	v_pk_fma_f32 v[58:59], v[58:59], v[152:153], v[160:161] op_sel_hi:[1,0,1]
	v_pk_fma_f32 v[60:61], v[60:61], v[152:153], v[162:163] op_sel_hi:[1,0,1]
	v_pk_fma_f32 v[54:55], v[54:55], v[152:153], v[156:157] op_sel:[0,1,0] op_sel_hi:[1,1,1]
	v_pk_fma_f32 v[56:57], v[56:57], v[152:153], v[158:159] op_sel:[0,1,0] op_sel_hi:[1,1,1]
	v_pk_fma_f32 v[50:51], v[50:51], v[152:153], v[160:161] op_sel:[0,1,0] op_sel_hi:[1,1,1]
	v_pk_fma_f32 v[52:53], v[52:53], v[152:153], v[162:163] op_sel:[0,1,0] op_sel_hi:[1,1,1]
	v_pk_fma_f32 v[38:39], v[38:39], v[154:155], v[156:157] op_sel_hi:[1,0,1]
	v_pk_fma_f32 v[40:41], v[40:41], v[154:155], v[158:159] op_sel_hi:[1,0,1]
	v_pk_fma_f32 v[34:35], v[34:35], v[154:155], v[160:161] op_sel_hi:[1,0,1]
	v_pk_fma_f32 v[36:37], v[36:37], v[154:155], v[162:163] op_sel_hi:[1,0,1]
	v_pk_fma_f32 v[22:23], v[22:23], v[154:155], v[156:157] op_sel:[0,1,0] op_sel_hi:[1,1,1]
	v_pk_fma_f32 v[24:25], v[24:25], v[154:155], v[158:159] op_sel:[0,1,0] op_sel_hi:[1,1,1]
	v_pk_fma_f32 v[18:19], v[18:19], v[154:155], v[160:161] op_sel:[0,1,0] op_sel_hi:[1,1,1]
	v_pk_fma_f32 v[20:21], v[20:21], v[154:155], v[162:163] op_sel:[0,1,0] op_sel_hi:[1,1,1]
	v_mul_f32_e32 v148, 0xbf317218, v148
	v_mul_f32_e32 v149, 0xbf317218, v149
	v_mul_f32_e32 v150, 0xbf317218, v150
	v_mul_f32_e32 v151, 0xbf317218, v151
	v_mul_f32_e32 v152, 0xbf317218, v152
	v_mul_f32_e32 v153, 0xbf317218, v153
	v_mul_f32_e32 v154, 0xbf317218, v154
	v_mul_f32_e32 v155, 0xbf317218, v155
	v_mul_f32_e32 v164, 0xbf317218, v164
	v_mul_f32_e32 v165, 0xbf317218, v165
	v_mul_f32_e32 v166, 0xbf317218, v166
	v_mul_f32_e32 v167, 0xbf317218, v167
	v_mul_f32_e32 v168, 0xbf317218, v168
	v_mul_f32_e32 v169, 0xbf317218, v169
	v_mul_f32_e32 v170, 0xbf317218, v170
	v_mul_f32_e32 v171, 0xbf317218, v171
	v_pk_fma_f32 v[106:107], v[106:107], v[148:149], v[164:165] op_sel_hi:[1,0,1]
	v_pk_fma_f32 v[108:109], v[108:109], v[148:149], v[166:167] op_sel_hi:[1,0,1]
	v_pk_fma_f32 v[98:99], v[98:99], v[148:149], v[168:169] op_sel_hi:[1,0,1]
	v_pk_fma_f32 v[100:101], v[100:101], v[148:149], v[170:171] op_sel_hi:[1,0,1]
	v_pk_fma_f32 v[90:91], v[90:91], v[148:149], v[164:165] op_sel:[0,1,0] op_sel_hi:[1,1,1]
	v_pk_fma_f32 v[92:93], v[92:93], v[148:149], v[166:167] op_sel:[0,1,0] op_sel_hi:[1,1,1]
	v_pk_fma_f32 v[82:83], v[82:83], v[148:149], v[168:169] op_sel:[0,1,0] op_sel_hi:[1,1,1]
	v_pk_fma_f32 v[84:85], v[84:85], v[148:149], v[170:171] op_sel:[0,1,0] op_sel_hi:[1,1,1]
	v_pk_fma_f32 v[78:79], v[78:79], v[150:151], v[164:165] op_sel_hi:[1,0,1]
	v_pk_fma_f32 v[80:81], v[80:81], v[150:151], v[166:167] op_sel_hi:[1,0,1]
	v_pk_fma_f32 v[74:75], v[74:75], v[150:151], v[168:169] op_sel_hi:[1,0,1]
	v_pk_fma_f32 v[76:77], v[76:77], v[150:151], v[170:171] op_sel_hi:[1,0,1]
	v_pk_fma_f32 v[70:71], v[70:71], v[150:151], v[164:165] op_sel:[0,1,0] op_sel_hi:[1,1,1]
	v_pk_fma_f32 v[72:73], v[72:73], v[150:151], v[166:167] op_sel:[0,1,0] op_sel_hi:[1,1,1]
	v_pk_fma_f32 v[66:67], v[66:67], v[150:151], v[168:169] op_sel:[0,1,0] op_sel_hi:[1,1,1]
	v_pk_fma_f32 v[68:69], v[68:69], v[150:151], v[170:171] op_sel:[0,1,0] op_sel_hi:[1,1,1]
	v_pk_fma_f32 v[46:47], v[46:47], v[152:153], v[164:165] op_sel_hi:[1,0,1]
	v_pk_fma_f32 v[48:49], v[48:49], v[152:153], v[166:167] op_sel_hi:[1,0,1]
	v_pk_fma_f32 v[42:43], v[42:43], v[152:153], v[168:169] op_sel_hi:[1,0,1]
	v_pk_fma_f32 v[44:45], v[44:45], v[152:153], v[170:171] op_sel_hi:[1,0,1]
	v_pk_fma_f32 v[30:31], v[30:31], v[152:153], v[164:165] op_sel:[0,1,0] op_sel_hi:[1,1,1]
	v_pk_fma_f32 v[32:33], v[32:33], v[152:153], v[166:167] op_sel:[0,1,0] op_sel_hi:[1,1,1]
	v_pk_fma_f32 v[26:27], v[26:27], v[152:153], v[168:169] op_sel:[0,1,0] op_sel_hi:[1,1,1]
	v_pk_fma_f32 v[28:29], v[28:29], v[152:153], v[170:171] op_sel:[0,1,0] op_sel_hi:[1,1,1]
	v_pk_fma_f32 v[14:15], v[14:15], v[154:155], v[164:165] op_sel_hi:[1,0,1]
	v_pk_fma_f32 v[16:17], v[16:17], v[154:155], v[166:167] op_sel_hi:[1,0,1]
	v_pk_fma_f32 v[10:11], v[10:11], v[154:155], v[168:169] op_sel_hi:[1,0,1]
	v_pk_fma_f32 v[12:13], v[12:13], v[154:155], v[170:171] op_sel_hi:[1,0,1]
	v_pk_fma_f32 v[6:7], v[6:7], v[154:155], v[164:165] op_sel:[0,1,0] op_sel_hi:[1,1,1]
	v_pk_fma_f32 v[8:9], v[8:9], v[154:155], v[166:167] op_sel:[0,1,0] op_sel_hi:[1,1,1]
	v_pk_fma_f32 v[2:3], v[2:3], v[154:155], v[168:169] op_sel:[0,1,0] op_sel_hi:[1,1,1]
	v_pk_fma_f32 v[4:5], v[4:5], v[154:155], v[170:171] op_sel:[0,1,0] op_sel_hi:[1,1,1]
	s_mov_b32 s14, 0xbfb8aa3b
	s_mov_b32 s15, 0xbfb8aa3b
	s_waitcnt vmcnt(0)
;     __device__ __forceinline__ void operator()(f32x4 (&acc)[2][2][4][2], const Unit& u, int wr, int wc, int fr, int fq) const {
;     ...
;         for (int n = 0; n < 2; ++n) {
;             constexpr float NL2E = -1.4426950408889634f;
;             const f32x4 w0 = *(const f32x4*)(fcw + ch + 4 * n) * NL2E, w1 = *(const f32x4*)(fcw + nch + ch + 4 * n) * NL2E, w2 = *(const f32x4*)(fcw + 2 * nch + ch + 4 * n) * NL2E, cb = *(const f32x4*)(fcb + ch + 4 * n) * NL2E;
; #pragma unroll
;             for (int e = 0; e < 4; ++e) {
;                 const float w0e = fr == 0 ? w0[e] : 0.f, w2e = fr == 15 ? w2[e] : 0.f;
;                 float tt[2][4];
; #pragma unroll
;                 for (int ai = 0; ai < 2; ++ai)
; #pragma unroll
;                     for (int m = 0; m < 4; ++m) { const float x = acc[ai][0][m][n][e];
;                         float t = __builtin_fmaf(w1[e], x, cb[e]); const float w0s = w0[e], w2s = w2[e];
;                         asm volatile("v_fmac_f32_dpp %0, %1, %2 row_shr:1 row_mask:0xf bank_mask:0xf bound_ctrl:1" : "+v"(t) : "v"(x), "v"(w0s));
;                         asm volatile("v_fmac_f32_dpp %0, %1, %2 row_shl:1 row_mask:0xf bank_mask:0xf bound_ctrl:1" : "+v"(t) : "v"(x), "v"(w2s));
;                         if (ai > 0 || m > 0) { const float xp = m > 0 ? acc[ai][0][m > 0 ? m - 1 : 0][n][e] : acc[0][0][3][n][e]; asm volatile("v_fmac_f32_dpp %0, %1, %2 row_ror:1 row_mask:0xf bank_mask:0xf" : "+v"(t) : "v"(xp), "v"(w0e)); }
;                         if (ai < 1 || m < 3) { const float xn = m < 3 ? acc[ai][0][m < 3 ? m + 1 : 3][n][e] : acc[1][0][0][n][e]; asm volatile("v_fmac_f32_dpp %0, %1, %2 row_ror:15 row_mask:0xf bank_mask:0xf" : "+v"(t) : "v"(xn), "v"(w2e)); }
;                         tt[ai][m] = t; }
; #pragma unroll
;                 for (int ai = 0; ai < 2; ++ai)
; #pragma unroll
;                     for (int m = 0; m < 4; ++m) { const float t = tt[ai][m];
;                         float res = (t * -0.6931471805599453f) * __builtin_amdgcn_rcpf(1.f + __builtin_amdgcn_exp2f(t)) * acc[ai][1][m][n][e];
;                         asm volatile("" : "+v"(res));
;                         acc[ai][0][m][n][e] = res;
;                     }
	v_pk_mul_f32 v[188:189], v[188:189], s[14:15]
	v_pk_mul_f32 v[190:191], v[190:191], s[14:15]
	v_pk_mul_f32 v[192:193], v[192:193], s[14:15]
	v_pk_mul_f32 v[194:195], v[194:195], s[14:15]
	v_pk_mul_f32 v[196:197], v[196:197], s[14:15]
	v_pk_mul_f32 v[198:199], v[198:199], s[14:15]
	v_pk_mul_f32 v[200:201], v[200:201], s[14:15]
	v_pk_mul_f32 v[202:203], v[202:203], s[14:15]
	v_pk_mul_f32 v[204:205], v[204:205], s[14:15]
	v_pk_mul_f32 v[206:207], v[206:207], s[14:15]
	v_pk_mul_f32 v[208:209], v[208:209], s[14:15]
	v_pk_mul_f32 v[210:211], v[210:211], s[14:15]
	v_pk_mul_f32 v[212:213], v[212:213], s[14:15]
	v_pk_mul_f32 v[214:215], v[214:215], s[14:15]
	v_pk_mul_f32 v[218:219], v[218:219], s[14:15]
	v_pk_mul_f32 v[220:221], v[220:221], s[14:15]
	v_pk_fma_f32 v[156:157], v[126:127], v[196:197], v[212:213]
	v_pk_fma_f32 v[158:159], v[118:119], v[196:197], v[212:213]
	v_pk_fma_f32 v[160:161], v[110:111], v[196:197], v[212:213]
	v_pk_fma_f32 v[162:163], v[94:95], v[196:197], v[212:213]
	v_pk_fma_f32 v[164:165], v[62:63], v[196:197], v[212:213]
	v_pk_fma_f32 v[166:167], v[54:55], v[196:197], v[212:213]
	v_pk_fma_f32 v[168:169], v[38:39], v[196:197], v[212:213]
	v_pk_fma_f32 v[170:171], v[22:23], v[196:197], v[212:213]
	v_pk_fma_f32 v[158:159], v[126:127], v[188:189], v[158:159]
	v_pk_fma_f32 v[160:161], v[118:119], v[188:189], v[160:161]
	v_pk_fma_f32 v[162:163], v[110:111], v[188:189], v[162:163]
	v_pk_fma_f32 v[164:165], v[94:95], v[188:189], v[164:165]
	v_pk_fma_f32 v[166:167], v[62:63], v[188:189], v[166:167]
	v_pk_fma_f32 v[168:169], v[54:55], v[188:189], v[168:169]
	v_pk_fma_f32 v[170:171], v[38:39], v[188:189], v[170:171]
	v_pk_fma_f32 v[156:157], v[118:119], v[204:205], v[156:157]
	v_pk_fma_f32 v[158:159], v[110:111], v[204:205], v[158:159]
	v_pk_fma_f32 v[160:161], v[94:95], v[204:205], v[160:161]
	v_pk_fma_f32 v[162:163], v[62:63], v[204:205], v[162:163]
	v_pk_fma_f32 v[164:165], v[54:55], v[204:205], v[164:165]
	v_pk_fma_f32 v[166:167], v[38:39], v[204:205], v[166:167]
	v_pk_fma_f32 v[168:169], v[22:23], v[204:205], v[168:169]
	v_fmac_f32_dpp v156, v22, v188 row_shr:1 row_mask:0xf bank_mask:0xf bound_ctrl:1
	v_fmac_f32_dpp v157, v23, v189 row_shr:1 row_mask:0xf bank_mask:0xf bound_ctrl:1
	v_fmac_f32_dpp v170, v126, v204 row_shl:1 row_mask:0xf bank_mask:0xf bound_ctrl:1
	v_fmac_f32_dpp v171, v127, v205 row_shl:1 row_mask:0xf bank_mask:0xf bound_ctrl:1
	v_exp_f32_e32 v222, v156
	v_exp_f32_e32 v223, v157
	v_exp_f32_e32 v224, v158
	v_exp_f32_e32 v225, v159
	v_exp_f32_e32 v226, v160
	v_exp_f32_e32 v227, v161
	v_exp_f32_e32 v228, v162
	v_exp_f32_e32 v229, v163
	v_exp_f32_e32 v230, v164
	v_exp_f32_e32 v231, v165
	v_exp_f32_e32 v232, v166
	v_exp_f32_e32 v233, v167
	v_exp_f32_e32 v234, v168
	v_exp_f32_e32 v235, v169
	v_exp_f32_e32 v186, v170
	v_exp_f32_e32 v187, v171
	v_pk_add_f32 v[222:223], v[222:223], s[26:27]
	v_pk_add_f32 v[224:225], v[224:225], s[26:27]
	v_pk_add_f32 v[226:227], v[226:227], s[26:27]
	v_pk_add_f32 v[228:229], v[228:229], s[26:27]
	v_pk_add_f32 v[230:231], v[230:231], s[26:27]
	v_pk_add_f32 v[232:233], v[232:233], s[26:27]
	v_pk_add_f32 v[234:235], v[234:235], s[26:27]
	v_pk_add_f32 v[186:187], v[186:187], s[26:27]
	v_rcp_f32_e32 v222, v222
	v_rcp_f32_e32 v223, v223
	v_rcp_f32_e32 v224, v224
	v_rcp_f32_e32 v225, v225
	v_rcp_f32_e32 v226, v226
	v_rcp_f32_e32 v227, v227
	v_rcp_f32_e32 v228, v228
	v_rcp_f32_e32 v229, v229
	v_rcp_f32_e32 v230, v230
	v_rcp_f32_e32 v231, v231
	v_rcp_f32_e32 v232, v232
	v_rcp_f32_e32 v233, v233
	v_rcp_f32_e32 v234, v234
	v_rcp_f32_e32 v235, v235
	v_rcp_f32_e32 v186, v186
	v_rcp_f32_e32 v187, v187
	v_pk_mul_f32 v[156:157], v[156:157], v[222:223]
	v_pk_mul_f32 v[158:159], v[158:159], v[224:225]
	v_pk_mul_f32 v[160:161], v[160:161], v[226:227]
	v_pk_mul_f32 v[162:163], v[162:163], v[228:229]
	v_pk_mul_f32 v[164:165], v[164:165], v[230:231]
	v_pk_mul_f32 v[166:167], v[166:167], v[232:233]
	v_pk_mul_f32 v[168:169], v[168:169], v[234:235]
	v_pk_mul_f32 v[170:171], v[170:171], v[186:187]
	v_pk_mul_f32 v[126:127], v[156:157], v[106:107]
	v_pk_mul_f32 v[118:119], v[158:159], v[90:91]
	v_pk_mul_f32 v[110:111], v[160:161], v[78:79]
	v_pk_mul_f32 v[94:95], v[162:163], v[70:71]
	v_pk_mul_f32 v[62:63], v[164:165], v[46:47]
	v_pk_mul_f32 v[54:55], v[166:167], v[30:31]
	v_pk_mul_f32 v[38:39], v[168:169], v[14:15]
	v_pk_mul_f32 v[22:23], v[170:171], v[6:7]
	v_pk_fma_f32 v[156:157], v[128:129], v[198:199], v[214:215]
	v_pk_fma_f32 v[158:159], v[120:121], v[198:199], v[214:215]
	v_pk_fma_f32 v[160:161], v[112:113], v[198:199], v[214:215]
	v_pk_fma_f32 v[162:163], v[96:97], v[198:199], v[214:215]
	v_pk_fma_f32 v[164:165], v[64:65], v[198:199], v[214:215]
	v_pk_fma_f32 v[166:167], v[56:57], v[198:199], v[214:215]
	v_pk_fma_f32 v[168:169], v[40:41], v[198:199], v[214:215]
	v_pk_fma_f32 v[170:171], v[24:25], v[198:199], v[214:215]
	v_pk_fma_f32 v[158:159], v[128:129], v[190:191], v[158:159]
	v_pk_fma_f32 v[160:161], v[120:121], v[190:191], v[160:161]
	v_pk_fma_f32 v[162:163], v[112:113], v[190:191], v[162:163]
	v_pk_fma_f32 v[164:165], v[96:97], v[190:191], v[164:165]
	v_pk_fma_f32 v[166:167], v[64:65], v[190:191], v[166:167]
	v_pk_fma_f32 v[168:169], v[56:57], v[190:191], v[168:169]
	v_pk_fma_f32 v[170:171], v[40:41], v[190:191], v[170:171]
	v_pk_fma_f32 v[156:157], v[120:121], v[206:207], v[156:157]
	v_pk_fma_f32 v[158:159], v[112:113], v[206:207], v[158:159]
	v_pk_fma_f32 v[160:161], v[96:97], v[206:207], v[160:161]
	v_pk_fma_f32 v[162:163], v[64:65], v[206:207], v[162:163]
	v_pk_fma_f32 v[164:165], v[56:57], v[206:207], v[164:165]
	v_pk_fma_f32 v[166:167], v[40:41], v[206:207], v[166:167]
;     __device__ __forceinline__ void operator()(f32x4 (&acc)[2][2][4][2], const Unit& u, int wr, int wc, int fr, int fq) const {
;     ...
;         for (int n = 0; n < 2; ++n) {
;             constexpr float NL2E = -1.4426950408889634f;
;             const f32x4 w0 = *(const f32x4*)(fcw + ch + 4 * n) * NL2E, w1 = *(const f32x4*)(fcw + nch + ch + 4 * n) * NL2E, w2 = *(const f32x4*)(fcw + 2 * nch + ch + 4 * n) * NL2E, cb = *(const f32x4*)(fcb + ch + 4 * n) * NL2E;
; #pragma unroll
;             for (int e = 0; e < 4; ++e) {
;                 const float w0e = fr == 0 ? w0[e] : 0.f, w2e = fr == 15 ? w2[e] : 0.f;
;                 float tt[2][4];
; #pragma unroll
;                 for (int ai = 0; ai < 2; ++ai)
; #pragma unroll
;                     for (int m = 0; m < 4; ++m) { const float x = acc[ai][0][m][n][e];
;                         float t = __builtin_fmaf(w1[e], x, cb[e]); const float w0s = w0[e], w2s = w2[e];
;                         asm volatile("v_fmac_f32_dpp %0, %1, %2 row_shr:1 row_mask:0xf bank_mask:0xf bound_ctrl:1" : "+v"(t) : "v"(x), "v"(w0s));
;                         asm volatile("v_fmac_f32_dpp %0, %1, %2 row_shl:1 row_mask:0xf bank_mask:0xf bound_ctrl:1" : "+v"(t) : "v"(x), "v"(w2s));
;                         if (ai > 0 || m > 0) { const float xp = m > 0 ? acc[ai][0][m > 0 ? m - 1 : 0][n][e] : acc[0][0][3][n][e]; asm volatile("v_fmac_f32_dpp %0, %1, %2 row_ror:1 row_mask:0xf bank_mask:0xf" : "+v"(t) : "v"(xp), "v"(w0e)); }
;                         if (ai < 1 || m < 3) { const float xn = m < 3 ? acc[ai][0][m < 3 ? m + 1 : 3][n][e] : acc[1][0][0][n][e]; asm volatile("v_fmac_f32_dpp %0, %1, %2 row_ror:15 row_mask:0xf bank_mask:0xf" : "+v"(t) : "v"(xn), "v"(w2e)); }
;                         tt[ai][m] = t; }
; #pragma unroll
;                 for (int ai = 0; ai < 2; ++ai)
; #pragma unroll
;                     for (int m = 0; m < 4; ++m) { const float t = tt[ai][m];
;                         float res = (t * -0.6931471805599453f) * __builtin_amdgcn_rcpf(1.f + __builtin_amdgcn_exp2f(t)) * acc[ai][1][m][n][e];
;                         asm volatile("" : "+v"(res));
;                         acc[ai][0][m][n][e] = res;
;                     }
	v_pk_fma_f32 v[168:169], v[24:25], v[206:207], v[168:169]
	v_fmac_f32_dpp v156, v24, v190 row_shr:1 row_mask:0xf bank_mask:0xf bound_ctrl:1
	v_fmac_f32_dpp v157, v25, v191 row_shr:1 row_mask:0xf bank_mask:0xf bound_ctrl:1
	v_fmac_f32_dpp v170, v128, v206 row_shl:1 row_mask:0xf bank_mask:0xf bound_ctrl:1
	v_fmac_f32_dpp v171, v129, v207 row_shl:1 row_mask:0xf bank_mask:0xf bound_ctrl:1
	v_exp_f32_e32 v222, v156
	v_exp_f32_e32 v223, v157
	v_exp_f32_e32 v224, v158
	v_exp_f32_e32 v225, v159
	v_exp_f32_e32 v226, v160
	v_exp_f32_e32 v227, v161
	v_exp_f32_e32 v228, v162
	v_exp_f32_e32 v229, v163
	v_exp_f32_e32 v230, v164
	v_exp_f32_e32 v231, v165
	v_exp_f32_e32 v232, v166
	v_exp_f32_e32 v233, v167
	v_exp_f32_e32 v234, v168
	v_exp_f32_e32 v235, v169
	v_exp_f32_e32 v186, v170
	v_exp_f32_e32 v187, v171
	v_pk_add_f32 v[222:223], v[222:223], s[26:27]
	v_pk_add_f32 v[224:225], v[224:225], s[26:27]
	v_pk_add_f32 v[226:227], v[226:227], s[26:27]
	v_pk_add_f32 v[228:229], v[228:229], s[26:27]
	v_pk_add_f32 v[230:231], v[230:231], s[26:27]
	v_pk_add_f32 v[232:233], v[232:233], s[26:27]
	v_pk_add_f32 v[234:235], v[234:235], s[26:27]
	v_pk_add_f32 v[186:187], v[186:187], s[26:27]
	v_rcp_f32_e32 v222, v222
	v_rcp_f32_e32 v223, v223
	v_rcp_f32_e32 v224, v224
	v_rcp_f32_e32 v225, v225
	v_rcp_f32_e32 v226, v226
	v_rcp_f32_e32 v227, v227
	v_rcp_f32_e32 v228, v228
	v_rcp_f32_e32 v229, v229
	v_rcp_f32_e32 v230, v230
	v_rcp_f32_e32 v231, v231
	v_rcp_f32_e32 v232, v232
	v_rcp_f32_e32 v233, v233
	v_rcp_f32_e32 v234, v234
	v_rcp_f32_e32 v235, v235
	v_rcp_f32_e32 v186, v186
	v_rcp_f32_e32 v187, v187
	v_pk_mul_f32 v[156:157], v[156:157], v[222:223]
	v_pk_mul_f32 v[158:159], v[158:159], v[224:225]
	v_pk_mul_f32 v[160:161], v[160:161], v[226:227]
	v_pk_mul_f32 v[162:163], v[162:163], v[228:229]
	v_pk_mul_f32 v[164:165], v[164:165], v[230:231]
	v_pk_mul_f32 v[166:167], v[166:167], v[232:233]
	v_pk_mul_f32 v[168:169], v[168:169], v[234:235]
	v_pk_mul_f32 v[170:171], v[170:171], v[186:187]
	v_pk_mul_f32 v[128:129], v[156:157], v[108:109]
	v_pk_mul_f32 v[120:121], v[158:159], v[92:93]
	v_pk_mul_f32 v[112:113], v[160:161], v[80:81]
	v_pk_mul_f32 v[96:97], v[162:163], v[72:73]
	v_pk_mul_f32 v[64:65], v[164:165], v[48:49]
	v_pk_mul_f32 v[56:57], v[166:167], v[32:33]
	v_pk_mul_f32 v[40:41], v[168:169], v[16:17]
	v_pk_mul_f32 v[24:25], v[170:171], v[8:9]
	v_pk_fma_f32 v[156:157], v[122:123], v[200:201], v[218:219]
	v_pk_fma_f32 v[158:159], v[114:115], v[200:201], v[218:219]
	v_pk_fma_f32 v[160:161], v[102:103], v[200:201], v[218:219]
	v_pk_fma_f32 v[162:163], v[86:87], v[200:201], v[218:219]
	v_pk_fma_f32 v[164:165], v[58:59], v[200:201], v[218:219]
	v_pk_fma_f32 v[166:167], v[50:51], v[200:201], v[218:219]
	v_pk_fma_f32 v[168:169], v[34:35], v[200:201], v[218:219]
	v_pk_fma_f32 v[170:171], v[18:19], v[200:201], v[218:219]
	v_pk_fma_f32 v[158:159], v[122:123], v[192:193], v[158:159]
	v_pk_fma_f32 v[160:161], v[114:115], v[192:193], v[160:161]
	v_pk_fma_f32 v[162:163], v[102:103], v[192:193], v[162:163]
	v_pk_fma_f32 v[164:165], v[86:87], v[192:193], v[164:165]
	v_pk_fma_f32 v[166:167], v[58:59], v[192:193], v[166:167]
	v_pk_fma_f32 v[168:169], v[50:51], v[192:193], v[168:169]
	v_pk_fma_f32 v[170:171], v[34:35], v[192:193], v[170:171]
	v_pk_fma_f32 v[156:157], v[114:115], v[208:209], v[156:157]
	v_pk_fma_f32 v[158:159], v[102:103], v[208:209], v[158:159]
	v_pk_fma_f32 v[160:161], v[86:87], v[208:209], v[160:161]
	v_pk_fma_f32 v[162:163], v[58:59], v[208:209], v[162:163]
	v_pk_fma_f32 v[164:165], v[50:51], v[208:209], v[164:165]
	v_pk_fma_f32 v[166:167], v[34:35], v[208:209], v[166:167]
	v_pk_fma_f32 v[168:169], v[18:19], v[208:209], v[168:169]
	v_fmac_f32_dpp v156, v18, v192 row_shr:1 row_mask:0xf bank_mask:0xf bound_ctrl:1
	v_fmac_f32_dpp v157, v19, v193 row_shr:1 row_mask:0xf bank_mask:0xf bound_ctrl:1
	v_fmac_f32_dpp v170, v122, v208 row_shl:1 row_mask:0xf bank_mask:0xf bound_ctrl:1
	v_fmac_f32_dpp v171, v123, v209 row_shl:1 row_mask:0xf bank_mask:0xf bound_ctrl:1
	v_exp_f32_e32 v222, v156
	v_exp_f32_e32 v223, v157
	v_exp_f32_e32 v224, v158
	v_exp_f32_e32 v225, v159
	v_exp_f32_e32 v226, v160
	v_exp_f32_e32 v227, v161
	v_exp_f32_e32 v228, v162
	v_exp_f32_e32 v229, v163
	v_exp_f32_e32 v230, v164
	v_exp_f32_e32 v231, v165
	v_exp_f32_e32 v232, v166
	v_exp_f32_e32 v233, v167
	v_exp_f32_e32 v234, v168
	v_exp_f32_e32 v235, v169
	v_exp_f32_e32 v186, v170
	v_exp_f32_e32 v187, v171
	v_pk_add_f32 v[222:223], v[222:223], s[26:27]
	v_pk_add_f32 v[224:225], v[224:225], s[26:27]
	v_pk_add_f32 v[226:227], v[226:227], s[26:27]
	v_pk_add_f32 v[228:229], v[228:229], s[26:27]
	v_pk_add_f32 v[230:231], v[230:231], s[26:27]
	v_pk_add_f32 v[232:233], v[232:233], s[26:27]
	v_pk_add_f32 v[234:235], v[234:235], s[26:27]
	v_pk_add_f32 v[186:187], v[186:187], s[26:27]
	v_rcp_f32_e32 v222, v222
	v_rcp_f32_e32 v223, v223
	v_rcp_f32_e32 v224, v224
	v_rcp_f32_e32 v225, v225
	v_rcp_f32_e32 v226, v226
	v_rcp_f32_e32 v227, v227
	v_rcp_f32_e32 v228, v228
	v_rcp_f32_e32 v229, v229
	v_rcp_f32_e32 v230, v230
	v_rcp_f32_e32 v231, v231
	v_rcp_f32_e32 v232, v232
	v_rcp_f32_e32 v233, v233
	v_rcp_f32_e32 v234, v234
	v_rcp_f32_e32 v235, v235
	v_rcp_f32_e32 v186, v186
	v_rcp_f32_e32 v187, v187
	v_pk_mul_f32 v[156:157], v[156:157], v[222:223]
	v_pk_mul_f32 v[158:159], v[158:159], v[224:225]
	v_pk_mul_f32 v[160:161], v[160:161], v[226:227]
	v_pk_mul_f32 v[162:163], v[162:163], v[228:229]
	v_pk_mul_f32 v[164:165], v[164:165], v[230:231]
	v_pk_mul_f32 v[166:167], v[166:167], v[232:233]
	v_pk_mul_f32 v[168:169], v[168:169], v[234:235]
	v_pk_mul_f32 v[170:171], v[170:171], v[186:187]
	v_pk_mul_f32 v[122:123], v[156:157], v[98:99]
;     __device__ __forceinline__ void operator()(f32x4 (&acc)[2][2][4][2], const Unit& u, int wr, int wc, int fr, int fq) const {
;     ...
;         for (int n = 0; n < 2; ++n) {
;             constexpr float NL2E = -1.4426950408889634f;
;             const f32x4 w0 = *(const f32x4*)(fcw + ch + 4 * n) * NL2E, w1 = *(const f32x4*)(fcw + nch + ch + 4 * n) * NL2E, w2 = *(const f32x4*)(fcw + 2 * nch + ch + 4 * n) * NL2E, cb = *(const f32x4*)(fcb + ch + 4 * n) * NL2E;
; #pragma unroll
;             for (int e = 0; e < 4; ++e) {
;                 const float w0e = fr == 0 ? w0[e] : 0.f, w2e = fr == 15 ? w2[e] : 0.f;
;                 float tt[2][4];
; #pragma unroll
;                 for (int ai = 0; ai < 2; ++ai)
; #pragma unroll
;                     for (int m = 0; m < 4; ++m) { const float x = acc[ai][0][m][n][e];
;                         float t = __builtin_fmaf(w1[e], x, cb[e]); const float w0s = w0[e], w2s = w2[e];
;                         asm volatile("v_fmac_f32_dpp %0, %1, %2 row_shr:1 row_mask:0xf bank_mask:0xf bound_ctrl:1" : "+v"(t) : "v"(x), "v"(w0s));
;                         asm volatile("v_fmac_f32_dpp %0, %1, %2 row_shl:1 row_mask:0xf bank_mask:0xf bound_ctrl:1" : "+v"(t) : "v"(x), "v"(w2s));
;                         if (ai > 0 || m > 0) { const float xp = m > 0 ? acc[ai][0][m > 0 ? m - 1 : 0][n][e] : acc[0][0][3][n][e]; asm volatile("v_fmac_f32_dpp %0, %1, %2 row_ror:1 row_mask:0xf bank_mask:0xf" : "+v"(t) : "v"(xp), "v"(w0e)); }
;                         if (ai < 1 || m < 3) { const float xn = m < 3 ? acc[ai][0][m < 3 ? m + 1 : 3][n][e] : acc[1][0][0][n][e]; asm volatile("v_fmac_f32_dpp %0, %1, %2 row_ror:15 row_mask:0xf bank_mask:0xf" : "+v"(t) : "v"(xn), "v"(w2e)); }
;                         tt[ai][m] = t; }
; #pragma unroll
;                 for (int ai = 0; ai < 2; ++ai)
; #pragma unroll
;                     for (int m = 0; m < 4; ++m) { const float t = tt[ai][m];
;                         float res = (t * -0.6931471805599453f) * __builtin_amdgcn_rcpf(1.f + __builtin_amdgcn_exp2f(t)) * acc[ai][1][m][n][e];
;                         asm volatile("" : "+v"(res));
;                         acc[ai][0][m][n][e] = res;
;                     }
;     ...
;                 const f32x4 a0 = acc[ai][0][2 * mp][0], a1 = acc[ai][0][2 * mp][1], c0 = acc[ai][0][2 * mp + 1][0], c1 = acc[ai][0][2 * mp + 1][1];
	v_pk_mul_f32 v[114:115], v[158:159], v[82:83]
	v_pk_mul_f32 v[102:103], v[160:161], v[74:75]
	v_pk_mul_f32 v[86:87], v[162:163], v[66:67]
	v_pk_mul_f32 v[58:59], v[164:165], v[42:43]
	v_pk_mul_f32 v[50:51], v[166:167], v[26:27]
	v_pk_mul_f32 v[34:35], v[168:169], v[10:11]
	v_pk_mul_f32 v[18:19], v[170:171], v[2:3]
	v_pk_fma_f32 v[156:157], v[124:125], v[202:203], v[220:221]
	v_pk_fma_f32 v[158:159], v[116:117], v[202:203], v[220:221]
	v_pk_fma_f32 v[160:161], v[104:105], v[202:203], v[220:221]
	v_pk_fma_f32 v[162:163], v[88:89], v[202:203], v[220:221]
	v_pk_fma_f32 v[164:165], v[60:61], v[202:203], v[220:221]
	v_pk_fma_f32 v[166:167], v[52:53], v[202:203], v[220:221]
	v_pk_fma_f32 v[168:169], v[36:37], v[202:203], v[220:221]
	v_pk_fma_f32 v[170:171], v[20:21], v[202:203], v[220:221]
	v_pk_fma_f32 v[158:159], v[124:125], v[194:195], v[158:159]
	v_pk_fma_f32 v[160:161], v[116:117], v[194:195], v[160:161]
	v_pk_fma_f32 v[162:163], v[104:105], v[194:195], v[162:163]
	v_pk_fma_f32 v[164:165], v[88:89], v[194:195], v[164:165]
	v_pk_fma_f32 v[166:167], v[60:61], v[194:195], v[166:167]
	v_pk_fma_f32 v[168:169], v[52:53], v[194:195], v[168:169]
	v_pk_fma_f32 v[170:171], v[36:37], v[194:195], v[170:171]
	v_pk_fma_f32 v[156:157], v[116:117], v[210:211], v[156:157]
	v_pk_fma_f32 v[158:159], v[104:105], v[210:211], v[158:159]
	v_pk_fma_f32 v[160:161], v[88:89], v[210:211], v[160:161]
	v_pk_fma_f32 v[162:163], v[60:61], v[210:211], v[162:163]
	v_pk_fma_f32 v[164:165], v[52:53], v[210:211], v[164:165]
	v_pk_fma_f32 v[166:167], v[36:37], v[210:211], v[166:167]
	v_pk_fma_f32 v[168:169], v[20:21], v[210:211], v[168:169]
	v_fmac_f32_dpp v156, v20, v194 row_shr:1 row_mask:0xf bank_mask:0xf bound_ctrl:1
	v_fmac_f32_dpp v157, v21, v195 row_shr:1 row_mask:0xf bank_mask:0xf bound_ctrl:1
	v_fmac_f32_dpp v170, v124, v210 row_shl:1 row_mask:0xf bank_mask:0xf bound_ctrl:1
	v_fmac_f32_dpp v171, v125, v211 row_shl:1 row_mask:0xf bank_mask:0xf bound_ctrl:1
	v_exp_f32_e32 v222, v156
	v_exp_f32_e32 v223, v157
	v_exp_f32_e32 v224, v158
	v_exp_f32_e32 v225, v159
	v_exp_f32_e32 v226, v160
	v_exp_f32_e32 v227, v161
	v_exp_f32_e32 v228, v162
	v_exp_f32_e32 v229, v163
	v_exp_f32_e32 v230, v164
	v_exp_f32_e32 v231, v165
	v_exp_f32_e32 v232, v166
	v_exp_f32_e32 v233, v167
	v_exp_f32_e32 v234, v168
	v_exp_f32_e32 v235, v169
	v_exp_f32_e32 v186, v170
	v_exp_f32_e32 v187, v171
	v_pk_add_f32 v[222:223], v[222:223], s[26:27]
	v_pk_add_f32 v[224:225], v[224:225], s[26:27]
	v_pk_add_f32 v[226:227], v[226:227], s[26:27]
	v_pk_add_f32 v[228:229], v[228:229], s[26:27]
	v_pk_add_f32 v[230:231], v[230:231], s[26:27]
	v_pk_add_f32 v[232:233], v[232:233], s[26:27]
	v_pk_add_f32 v[234:235], v[234:235], s[26:27]
	v_pk_add_f32 v[186:187], v[186:187], s[26:27]
	v_rcp_f32_e32 v222, v222
	v_rcp_f32_e32 v223, v223
	v_rcp_f32_e32 v224, v224
	v_rcp_f32_e32 v225, v225
	v_rcp_f32_e32 v226, v226
	v_rcp_f32_e32 v227, v227
	v_rcp_f32_e32 v228, v228
	v_rcp_f32_e32 v229, v229
	v_rcp_f32_e32 v230, v230
	v_rcp_f32_e32 v231, v231
	v_rcp_f32_e32 v232, v232
	v_rcp_f32_e32 v233, v233
	v_rcp_f32_e32 v234, v234
	v_rcp_f32_e32 v235, v235
	v_rcp_f32_e32 v186, v186
	v_rcp_f32_e32 v187, v187
	v_pk_mul_f32 v[156:157], v[156:157], v[222:223]
	v_pk_mul_f32 v[158:159], v[158:159], v[224:225]
	v_pk_mul_f32 v[160:161], v[160:161], v[226:227]
	v_pk_mul_f32 v[162:163], v[162:163], v[228:229]
	v_pk_mul_f32 v[164:165], v[164:165], v[230:231]
	v_pk_mul_f32 v[166:167], v[166:167], v[232:233]
	v_pk_mul_f32 v[168:169], v[168:169], v[234:235]
	v_pk_mul_f32 v[170:171], v[170:171], v[186:187]
	v_pk_mul_f32 v[124:125], v[156:157], v[100:101]
	v_pk_mul_f32 v[116:117], v[158:159], v[84:85]
	v_pk_mul_f32 v[104:105], v[160:161], v[76:77]
	v_pk_mul_f32 v[88:89], v[162:163], v[68:69]
	v_pk_mul_f32 v[60:61], v[164:165], v[44:45]
	v_pk_mul_f32 v[52:53], v[166:167], v[28:29]
	v_pk_mul_f32 v[36:37], v[168:169], v[12:13]
	v_pk_mul_f32 v[20:21], v[170:171], v[4:5]
	v_med3_f32 v126, v126, s81, v184
	v_med3_f32 v127, v127, s81, v184
	v_med3_f32 v128, v128, s81, v184
	v_med3_f32 v129, v129, s81, v184
;     __device__ __forceinline__ void operator()(f32x4 (&acc)[2][2][4][2], const Unit& u, int wr, int wc, int fr, int fq) const {
;     ...
; #pragma unroll
;         for (int ai = 0; ai < 2; ++ai)
; #pragma unroll
;             for (int mp = 0; mp < 2; ++mp) {
;                 const f32x4 a0 = acc[ai][0][2 * mp][0], a1 = acc[ai][0][2 * mp][1], c0 = acc[ai][0][2 * mp + 1][0], c1 = acc[ai][0][2 * mp + 1][1];
;                 unsigned ax = cvt_pk4_fp8(a0[0], a0[1], a0[2], a0[3]), ay = cvt_pk4_fp8(a1[0], a1[1], a1[2], a1[3]), cx = cvt_pk4_fp8(c0[0], c0[1], c0[2], c0[3]), cy = cvt_pk4_fp8(c1[0], c1[1], c1[2], c1[3]);
;                 asm volatile("s_nop 1\n\tv_permlane16_swap_b32 %0, %1" : "+v"(ax), "+v"(cx)); asm volatile("s_nop 1\n\tv_permlane16_swap_b32 %0, %1" : "+v"(ay), "+v"(cy));
;                 const int od = fq & 1, lr = 64 * ai + 16 * (2 * mp + od) + fr;
;                 u32x4 w; w.x = ax; w.y = ay; w.z = cx; w.w = cy;
;                 *(u32x4*)((unsigned char*)ACT + (tok00 + (size_t)lr * 64) * lda + ch - 8 * od) = w; }
	v_med3_f32 v122, v122, s81, v184
	v_med3_f32 v123, v123, s81, v184
	v_med3_f32 v124, v124, s81, v184
	v_med3_f32 v125, v125, s81, v184
	v_med3_f32 v118, v118, s81, v184
	v_med3_f32 v119, v119, s81, v184
	v_med3_f32 v120, v120, s81, v184
	v_med3_f32 v121, v121, s81, v184
	v_med3_f32 v114, v114, s81, v184
	v_med3_f32 v115, v115, s81, v184
	v_med3_f32 v116, v116, s81, v184
	v_med3_f32 v117, v117, s81, v184
	v_cvt_pk_fp8_f32 v148, v126, v127
	v_cvt_pk_fp8_f32 v148, v128, v129 op_sel:[0,0,1]
	v_cvt_pk_fp8_f32 v149, v122, v123
	v_cvt_pk_fp8_f32 v149, v124, v125 op_sel:[0,0,1]
	v_cvt_pk_fp8_f32 v150, v118, v119
	v_cvt_pk_fp8_f32 v150, v120, v121 op_sel:[0,0,1]
	v_cvt_pk_fp8_f32 v151, v114, v115
	v_cvt_pk_fp8_f32 v151, v116, v117 op_sel:[0,0,1]
	s_nop 1
	v_permlane16_swap_b32 v148, v150
	v_permlane16_swap_b32 v149, v151
	global_store_dwordx4 v185, v[148:151], s[28:29]
	v_med3_f32 v110, v110, s81, v184
	v_med3_f32 v111, v111, s81, v184
	v_med3_f32 v112, v112, s81, v184
	v_med3_f32 v113, v113, s81, v184
	v_med3_f32 v102, v102, s81, v184
	v_med3_f32 v103, v103, s81, v184
	v_med3_f32 v104, v104, s81, v184
	v_med3_f32 v105, v105, s81, v184
	v_med3_f32 v94, v94, s81, v184
	v_med3_f32 v95, v95, s81, v184
	v_med3_f32 v96, v96, s81, v184
	v_med3_f32 v97, v97, s81, v184
	v_med3_f32 v86, v86, s81, v184
	v_med3_f32 v87, v87, s81, v184
	v_med3_f32 v88, v88, s81, v184
	v_med3_f32 v89, v89, s81, v184
	v_cvt_pk_fp8_f32 v152, v110, v111
	v_cvt_pk_fp8_f32 v152, v112, v113 op_sel:[0,0,1]
	v_cvt_pk_fp8_f32 v153, v102, v103
	v_cvt_pk_fp8_f32 v153, v104, v105 op_sel:[0,0,1]
	v_cvt_pk_fp8_f32 v154, v94, v95
	v_cvt_pk_fp8_f32 v154, v96, v97 op_sel:[0,0,1]
	v_cvt_pk_fp8_f32 v155, v86, v87
	v_cvt_pk_fp8_f32 v155, v88, v89 op_sel:[0,0,1]
	v_add_u32_e32 v185, 0xb0000, v185
	s_nop 1
	v_permlane16_swap_b32 v152, v154
	v_permlane16_swap_b32 v153, v155
	global_store_dwordx4 v185, v[152:155], s[28:29]
	v_med3_f32 v62, v62, s81, v184
	v_med3_f32 v63, v63, s81, v184
	v_med3_f32 v64, v64, s81, v184
	v_med3_f32 v65, v65, s81, v184
	v_med3_f32 v58, v58, s81, v184
	v_med3_f32 v59, v59, s81, v184
	v_med3_f32 v60, v60, s81, v184
	v_med3_f32 v61, v61, s81, v184
	v_med3_f32 v54, v54, s81, v184
	v_med3_f32 v55, v55, s81, v184
	v_med3_f32 v56, v56, s81, v184
	v_med3_f32 v57, v57, s81, v184
	v_med3_f32 v50, v50, s81, v184
	v_med3_f32 v51, v51, s81, v184
	v_med3_f32 v52, v52, s81, v184
	v_med3_f32 v53, v53, s81, v184
	v_cvt_pk_fp8_f32 v148, v62, v63
	v_cvt_pk_fp8_f32 v148, v64, v65 op_sel:[0,0,1]
	v_cvt_pk_fp8_f32 v149, v58, v59
	v_cvt_pk_fp8_f32 v149, v60, v61 op_sel:[0,0,1]
	v_cvt_pk_fp8_f32 v150, v54, v55
	v_cvt_pk_fp8_f32 v150, v56, v57 op_sel:[0,0,1]
	v_cvt_pk_fp8_f32 v151, v50, v51
	v_cvt_pk_fp8_f32 v151, v52, v53 op_sel:[0,0,1]
	v_add_u32_e32 v185, 0xb0000, v185
	s_nop 1
	v_permlane16_swap_b32 v148, v150
	v_permlane16_swap_b32 v149, v151
	global_store_dwordx4 v185, v[148:151], s[28:29]
	v_med3_f32 v38, v38, s81, v184
	v_med3_f32 v39, v39, s81, v184
	v_med3_f32 v40, v40, s81, v184
	v_med3_f32 v41, v41, s81, v184
	v_med3_f32 v34, v34, s81, v184
	v_med3_f32 v35, v35, s81, v184
	v_med3_f32 v36, v36, s81, v184
	v_med3_f32 v37, v37, s81, v184
	v_med3_f32 v22, v22, s81, v184
	v_med3_f32 v23, v23, s81, v184
	v_med3_f32 v24, v24, s81, v184
	v_med3_f32 v25, v25, s81, v184
	v_med3_f32 v18, v18, s81, v184
	v_med3_f32 v19, v19, s81, v184
	v_med3_f32 v20, v20, s81, v184
	v_med3_f32 v21, v21, s81, v184
	v_cvt_pk_fp8_f32 v152, v38, v39
	v_cvt_pk_fp8_f32 v152, v40, v41 op_sel:[0,0,1]
	v_cvt_pk_fp8_f32 v153, v34, v35
	v_cvt_pk_fp8_f32 v153, v36, v37 op_sel:[0,0,1]
	v_cvt_pk_fp8_f32 v154, v22, v23
	v_cvt_pk_fp8_f32 v154, v24, v25 op_sel:[0,0,1]
	v_cvt_pk_fp8_f32 v155, v18, v19
	v_cvt_pk_fp8_f32 v155, v20, v21 op_sel:[0,0,1]
	v_add_u32_e32 v185, 0xb0000, v185
	s_nop 1
	v_permlane16_swap_b32 v152, v154
	v_permlane16_swap_b32 v153, v155
	global_store_dwordx4 v185, v[152:155], s[28:29]
	s_and_b64 vcc, exec, s[4:5]
	s_mov_b64 s[4:5], -1
	s_cbranch_vccnz .LBB0_911
	s_andn2_b64 vcc, exec, s[12:13]
	s_cbranch_vccnz .LBB0_910
	s_barrier
	s_branch .LBB0_910
